# J1 + w_in GEMM second round split into 256 column-half units (bj=1 MFMA block skipped in half mode)
# speedup vs baseline: 1.0574x; 1.0060x over previous
.LBB0_471:
	s_add_u32 s8, s16, 0x10b00000
	s_addc_u32 s9, s17, 0
	s_lshl_b32 s11, s11, 5
	s_and_b32 s65, s11, 0x60
	s_add_i32 m0, s60, 0x18000
	v_lshl_add_u64 v[6:7], v[6:7], 0, s[12:13]
	s_lshl_b32 s64, s14, 6
	s_lshl_b32 s16, s14, 13
	s_lshl_b32 s11, s65, 7
	s_waitcnt vmcnt(2)
	s_barrier
	global_load_lds_dwordx4 v[6:7], off
	v_lshl_add_u64 v[4:5], v[4:5], 0, s[12:13]
	s_add_i32 m0, s60, 0x1a000
	s_add_i32 s66, s60, 0x8000
	s_add_i32 s67, s60, 0xa000
	global_load_lds_dwordx4 v[4:5], off
	v_lshl_add_u64 v[0:1], v[0:1], 0, s[12:13]
	s_mov_b32 m0, s66
	s_add_u32 s14, s0, 0x40080
	global_load_lds_dwordx4 v[0:1], off
	v_lshl_add_u64 v[0:1], v[2:3], 0, s[12:13]
	s_mov_b32 m0, s67
	s_addc_u32 s15, s1, 0
	global_load_lds_dwordx4 v[0:1], off
	s_add_i32 m0, s60, 0x1c000
	v_lshl_add_u64 v[0:1], s[14:15], 0, v[80:81]
	global_load_lds_dwordx4 v[0:1], off
	v_lshl_add_u64 v[0:1], s[14:15], 0, v[130:131]
	s_add_i32 m0, s60, 0x1e000
	s_movk_i32 s14, 0x3c0
	global_load_lds_dwordx4 v[0:1], off
	v_and_b32_e32 v0, 48, v8
	v_lshlrev_b32_e32 v1, 6, v8
	v_and_or_b32 v0, v1, s14, v0
	v_lshlrev_b32_e32 v1, 2, v8
	v_and_b32_e32 v1, 32, v1
	v_bitop3_b32 v2, v0, s16, v1 bitop3:0xde
	v_bitop3_b32 v144, s11, v0, v1 bitop3:0xf6
	v_lshlrev_b32_e32 v0, 14, v9
	v_and_b32_e32 v0, 0xffff8000, v0
	v_lshl_add_u32 v0, v10, 11, v0
	v_and_b32_e32 v1, 1, v9
	v_lshl_or_b32 v0, v1, 6, v0
	v_lshl_add_u32 v136, v11, 1, v0
	v_lshlrev_b32_e32 v0, 14, v13
	v_and_b32_e32 v0, 0xffff8000, v0
	s_waitcnt vmcnt(6)
	v_lshl_add_u32 v0, v12, 11, v0
	v_and_b32_e32 v1, 1, v13
	s_cmpk_lt_u32 s10, 0x100
	v_lshl_or_b32 v0, v1, 6, v0
	v_readlane_b32 s14, v254, 54
	s_cselect_b64 s[10:11], -1, 0
	s_waitcnt lgkmcnt(0)
	s_ashr_i32 s70, s79, 31
	v_mov_b32_e32 v137, v81
	v_lshl_add_u32 v138, v14, 1, v0
	v_mov_b32_e32 v139, v81
	s_mov_b32 s71, 0
	s_mov_b32 s100, 0
	s_mov_b32 s101, 0
	v_add_u32_e32 v145, 0, v2
	v_readlane_b32 s78, v254, 46
	s_mov_b32 s77, s14
	s_barrier
	v_readlane_b32 s15, v254, 55
	s_branch .LBB0_474

.LBB0_473:
	s_andn2_b64 vcc, exec, s[0:1]
	s_mov_b32 s101, s100
	s_mov_b32 s100, 0
	s_mov_b32 s78, s14
	s_mov_b32 s77, s16
	s_mov_b64 s[0:1], s[26:27]
	s_mov_b64 s[6:7], s[22:23]
	s_cbranch_vccz .LBB0_515
.LBB0_474:
	s_add_i32 s71, s71, 1
	s_mul_i32 s15, s71, s70
	s_mul_hi_u32 s17, s71, s79
	s_add_i32 s17, s17, s15
	s_mul_i32 s15, s71, s79
	s_add_u32 s22, s15, s33
	v_readlane_b32 s15, v252, 0
	s_addc_u32 s23, s17, s15
	s_cmp_lg_u32 s71, 1
	s_cbranch_scc1 .Lk0_Ldone
	s_cmpk_lg_u32 s79, 0x100
	s_cbranch_scc1 .Lk0_Ldone
	s_and_b32 s22, s33, 7
	s_lshr_b32 s23, s33, 4
	s_lshl_b32 s23, s23, 3
	s_add_i32 s22, s22, s23
	s_addk_i32 s22, 0x100
	s_mov_b32 s23, 0
	s_mov_b32 s100, 1
.Lk0_Ldone:
	v_cmp_gt_i64_e32 vcc, s[22:23], v[248:249]
	v_cmp_lt_i64_e64 s[36:37], s[22:23], v[246:247]
	s_cbranch_vccnz .LBB0_476
	s_ashr_i32 s14, s22, 31
	s_lshr_b32 s14, s14, 29
	s_add_i32 s14, s22, s14
	s_ashr_i32 s15, s14, 3
	s_and_b32 s14, s14, -8
	s_sub_i32 s14, s22, s14
	s_cmp_lt_i32 s14, 0
	s_cselect_b32 s16, 49, 48
	s_mul_i32 s14, s14, s16
	s_add_i32 s14, s14, s15
	s_ashr_i32 s15, s14, 31
	s_lshr_b32 s15, s15, 26
	s_add_i32 s15, s14, s15
	s_ashr_i32 s16, s15, 6
	s_lshl_b32 s16, s16, 3
	s_sub_i32 s17, 48, s16
	s_min_i32 s17, s17, 8
	s_abs_i32 s22, s17
	v_cvt_f32_u32_e32 v0, s22
	s_sub_i32 s26, 0, s22
	s_andn2_b32 s15, s15, 63
	s_sub_i32 s15, s14, s15
	v_rcp_iflag_f32_e32 v0, v0
	s_abs_i32 s14, s15
	s_xor_b32 s23, s15, s17
	s_ashr_i32 s23, s23, 31
	v_mul_f32_e32 v0, 0x4f7ffffe, v0
	v_cvt_u32_f32_e32 v0, v0
	s_nop 0
	v_readfirstlane_b32 s27, v0
	s_mul_i32 s26, s26, s27
	s_mul_hi_u32 s26, s27, s26
	s_add_i32 s27, s27, s26
	s_mul_hi_u32 s26, s14, s27
	s_mul_i32 s27, s26, s22
	s_sub_i32 s14, s14, s27
	s_add_i32 s30, s26, 1
	s_sub_i32 s27, s14, s22
	s_cmp_ge_u32 s14, s22
	s_cselect_b32 s26, s30, s26
	s_cselect_b32 s14, s27, s14
	s_add_i32 s27, s26, 1
	s_cmp_ge_u32 s14, s22
	s_cselect_b32 s14, s27, s26
	s_xor_b32 s14, s14, s23
	s_sub_i32 s14, s14, s23
	s_mul_i32 s17, s14, s17
	s_sub_i32 s15, s15, s17
	s_add_i32 s16, s16, s15
.LBB0_476:
	s_ashr_i32 s17, s16, 31
	s_lshl_b64 s[22:23], s[16:17], 19
	s_add_u32 s22, s18, s22
	s_addc_u32 s23, s34, s23
	s_and_b64 s[26:27], s[36:37], exec
	s_cselect_b32 s17, s23, s7
	s_cselect_b32 s80, s22, s6
	s_ashr_i32 s15, s14, 31
	s_lshl_b64 s[26:27], s[14:15], 19
	s_add_u32 s26, s35, s26
	s_addc_u32 s27, s38, s27
	s_cmp_lg_u32 s100, 1
	s_cbranch_scc1 .Lk0_nbdone
	s_bfe_u32 s30, s33, 0x10003
	s_lshl_b32 s30, s30, 18
	s_add_u32 s26, s26, s30
	s_addc_u32 s27, s27, 0
.Lk0_nbdone:
	s_and_b64 s[30:31], s[36:37], exec
	s_cselect_b32 s15, s27, s1
	s_cselect_b32 s81, s26, s0
	s_add_u32 s82, s0, 0x100
	s_addc_u32 s83, s1, 0
	s_add_u32 s0, s6, 0x40080
	v_mov_b32_e32 v0, 0
	s_addc_u32 s1, s7, 0
	s_mov_b32 s84, -2
	v_mov_b32_e32 v1, v0
	v_mov_b32_e32 v2, v0
	v_mov_b32_e32 v3, v0
	v_mov_b32_e32 v4, v0
	v_mov_b32_e32 v5, v0
	v_mov_b32_e32 v6, v0
	v_mov_b32_e32 v7, v0
	v_mov_b32_e32 v12, v0
	v_mov_b32_e32 v13, v0
	v_mov_b32_e32 v14, v0
	v_mov_b32_e32 v15, v0
	v_mov_b32_e32 v20, v0
	v_mov_b32_e32 v21, v0
	v_mov_b32_e32 v22, v0
	v_mov_b32_e32 v23, v0
	v_mov_b32_e32 v28, v0
	v_mov_b32_e32 v29, v0
	v_mov_b32_e32 v30, v0
	v_mov_b32_e32 v31, v0
	v_mov_b32_e32 v36, v0
	v_mov_b32_e32 v37, v0
	v_mov_b32_e32 v38, v0
	v_mov_b32_e32 v39, v0
	v_mov_b32_e32 v44, v0
	v_mov_b32_e32 v45, v0
	v_mov_b32_e32 v46, v0
	v_mov_b32_e32 v47, v0
	v_mov_b32_e32 v52, v0
	v_mov_b32_e32 v53, v0
	v_mov_b32_e32 v54, v0
	v_mov_b32_e32 v55, v0
	v_mov_b32_e32 v8, v0
	v_mov_b32_e32 v9, v0
	v_mov_b32_e32 v10, v0
	v_mov_b32_e32 v11, v0
	v_mov_b32_e32 v16, v0
	v_mov_b32_e32 v17, v0
	v_mov_b32_e32 v18, v0
	v_mov_b32_e32 v19, v0
	v_mov_b32_e32 v24, v0
	v_mov_b32_e32 v25, v0
	v_mov_b32_e32 v26, v0
	v_mov_b32_e32 v27, v0
	v_mov_b32_e32 v32, v0
	v_mov_b32_e32 v33, v0
	v_mov_b32_e32 v34, v0
	v_mov_b32_e32 v35, v0
	v_mov_b32_e32 v40, v0
	v_mov_b32_e32 v41, v0
	v_mov_b32_e32 v42, v0
	v_mov_b32_e32 v43, v0
	v_mov_b32_e32 v48, v0
	v_mov_b32_e32 v49, v0
	v_mov_b32_e32 v50, v0
	v_mov_b32_e32 v51, v0
	v_mov_b32_e32 v56, v0
	v_mov_b32_e32 v57, v0
	v_mov_b32_e32 v58, v0
	v_mov_b32_e32 v59, v0
	v_mov_b32_e32 v60, v0
	v_mov_b32_e32 v61, v0
	v_mov_b32_e32 v62, v0
	v_mov_b32_e32 v63, v0
	v_mov_b32_e32 v64, v0
	v_mov_b32_e32 v65, v0
	v_mov_b32_e32 v66, v0
	v_mov_b32_e32 v67, v0
	v_mov_b32_e32 v68, v0
	v_mov_b32_e32 v69, v0
	v_mov_b32_e32 v70, v0
	v_mov_b32_e32 v71, v0
	v_mov_b32_e32 v76, v0
	v_mov_b32_e32 v77, v0
	v_mov_b32_e32 v78, v0
	v_mov_b32_e32 v79, v0
	v_mov_b32_e32 v86, v0
	v_mov_b32_e32 v87, v0
	v_mov_b32_e32 v88, v0
	v_mov_b32_e32 v89, v0
	v_mov_b32_e32 v94, v0
	v_mov_b32_e32 v95, v0
	v_mov_b32_e32 v96, v0
	v_mov_b32_e32 v97, v0
	v_mov_b32_e32 v102, v0
	v_mov_b32_e32 v103, v0
	v_mov_b32_e32 v104, v0
	v_mov_b32_e32 v105, v0
	v_mov_b32_e32 v110, v0
	v_mov_b32_e32 v111, v0
	v_mov_b32_e32 v112, v0
	v_mov_b32_e32 v113, v0
	v_mov_b32_e32 v118, v0
	v_mov_b32_e32 v119, v0
	v_mov_b32_e32 v120, v0
	v_mov_b32_e32 v121, v0
	v_mov_b32_e32 v72, v0
	v_mov_b32_e32 v73, v0
	v_mov_b32_e32 v74, v0
	v_mov_b32_e32 v75, v0
	v_mov_b32_e32 v82, v0
	v_mov_b32_e32 v83, v0
	v_mov_b32_e32 v84, v0
	v_mov_b32_e32 v85, v0
	v_mov_b32_e32 v90, v0
	v_mov_b32_e32 v91, v0
	v_mov_b32_e32 v92, v0
	v_mov_b32_e32 v93, v0
	v_mov_b32_e32 v98, v0
	v_mov_b32_e32 v99, v0
	v_mov_b32_e32 v100, v0
	v_mov_b32_e32 v101, v0
	v_mov_b32_e32 v106, v0
	v_mov_b32_e32 v107, v0
	v_mov_b32_e32 v108, v0
	v_mov_b32_e32 v109, v0
	v_mov_b32_e32 v114, v0
	v_mov_b32_e32 v115, v0
	v_mov_b32_e32 v116, v0
	v_mov_b32_e32 v117, v0
	v_mov_b32_e32 v122, v0
	v_mov_b32_e32 v123, v0
	v_mov_b32_e32 v124, v0
	v_mov_b32_e32 v125, v0
	v_mov_b32_e32 v126, v0
	v_mov_b32_e32 v127, v0
	v_mov_b32_e32 v128, v0
	v_mov_b32_e32 v129, v0
.LBB0_477:
	s_add_u32 s6, s0, 0xfffc0080
	s_addc_u32 s7, s1, -1
	s_add_i32 s85, 0, 0x10000
	s_cmp_eq_u32 s84, 12
	s_cselect_b32 s31, s17, s7
	s_cselect_b32 s30, s80, s6
	s_cselect_b32 s7, s15, s83
	s_cselect_b32 s6, s81, s82
	s_add_i32 s88, 0, 0x14000
	v_add_u32_e32 v154, s85, v144
	v_add_u32_e32 v170, s88, v144
	.p2align 6
	ds_read_b128 v[140:143], v154
	ds_read_b128 v[146:149], v154 offset:1024
	ds_read_b128 v[150:153], v154 offset:2048
	ds_read_b128 v[154:157], v154 offset:3072
	ds_read_b128 v[158:161], v170
	ds_read_b128 v[162:165], v170 offset:1024
	ds_read_b128 v[166:169], v170 offset:2048
	ds_read_b128 v[170:173], v170 offset:3072
	v_lshl_add_u64 v[182:183], s[0:1], 0, v[138:139]
	s_add_i32 m0, s60, 0xc000
	ds_read_b128 v[174:177], v145
	ds_read_b128 v[178:181], v145 offset:1024
	ds_read_b128 v[200:203], v145 offset:2048
	ds_read_b128 v[204:207], v145 offset:3072
	ds_read_b128 v[208:211], v145 offset:4096
	ds_read_b128 v[212:215], v145 offset:5120
	ds_read_b128 v[222:225], v145 offset:6144
	ds_read_b128 v[226:229], v145 offset:7168
	global_load_lds_dwordx4 v[182:183], off
	v_lshl_add_u64 v[182:183], s[0:1], 0, v[136:137]
	s_add_i32 m0, s60, 0xe000
	s_nop 0
	global_load_lds_dwordx4 v[182:183], off
	s_waitcnt vmcnt(8)
	s_waitcnt lgkmcnt(0)
	s_barrier
	s_setprio 1
	s_waitcnt lgkmcnt(0)
	v_mfma_f32_16x16x32_bf16 v[126:129], v[140:143], v[174:177], v[126:129]
	v_mfma_f32_16x16x32_bf16 v[122:125], v[150:153], v[174:177], v[122:125]
	v_mfma_f32_16x16x32_bf16 v[114:117], v[140:143], v[200:203], v[114:117]
	v_mfma_f32_16x16x32_bf16 v[106:109], v[150:153], v[200:203], v[106:109]
	v_mfma_f32_16x16x32_bf16 v[98:101], v[140:143], v[208:211], v[98:101]
	v_mfma_f32_16x16x32_bf16 v[90:93], v[150:153], v[208:211], v[90:93]
	v_mfma_f32_16x16x32_bf16 v[82:85], v[140:143], v[222:225], v[82:85]
	v_mfma_f32_16x16x32_bf16 v[72:75], v[150:153], v[222:225], v[72:75]
	v_mfma_f32_16x16x32_bf16 v[126:129], v[146:149], v[178:181], v[126:129]
	v_mfma_f32_16x16x32_bf16 v[122:125], v[154:157], v[178:181], v[122:125]
	v_mfma_f32_16x16x32_bf16 v[114:117], v[146:149], v[204:207], v[114:117]
	v_mfma_f32_16x16x32_bf16 v[106:109], v[154:157], v[204:207], v[106:109]
	v_mfma_f32_16x16x32_bf16 v[98:101], v[146:149], v[212:215], v[98:101]
	v_mfma_f32_16x16x32_bf16 v[90:93], v[154:157], v[212:215], v[90:93]
	v_mfma_f32_16x16x32_bf16 v[82:85], v[146:149], v[226:229], v[82:85]
	v_mfma_f32_16x16x32_bf16 v[72:75], v[154:157], v[226:229], v[72:75]
	s_setprio 0
	s_cmp_eq_u32 s101, 1
	s_cbranch_scc1 .Lk0_half1
	s_setprio 1
	v_mfma_f32_16x16x32_bf16 v[118:121], v[158:161], v[174:177], v[118:121]
	v_mfma_f32_16x16x32_bf16 v[110:113], v[166:169], v[174:177], v[110:113]
	v_mfma_f32_16x16x32_bf16 v[102:105], v[158:161], v[200:203], v[102:105]
	v_mfma_f32_16x16x32_bf16 v[94:97], v[166:169], v[200:203], v[94:97]
	v_mfma_f32_16x16x32_bf16 v[86:89], v[158:161], v[208:211], v[86:89]
	v_mfma_f32_16x16x32_bf16 v[76:79], v[166:169], v[208:211], v[76:79]
	v_mfma_f32_16x16x32_bf16 v[68:71], v[158:161], v[222:225], v[68:71]
	v_mfma_f32_16x16x32_bf16 v[64:67], v[166:169], v[222:225], v[64:67]
	v_mfma_f32_16x16x32_bf16 v[118:121], v[162:165], v[178:181], v[118:121]
	v_mfma_f32_16x16x32_bf16 v[110:113], v[170:173], v[178:181], v[110:113]
	v_mfma_f32_16x16x32_bf16 v[102:105], v[162:165], v[204:207], v[102:105]
	v_mfma_f32_16x16x32_bf16 v[94:97], v[170:173], v[204:207], v[94:97]
	v_mfma_f32_16x16x32_bf16 v[86:89], v[162:165], v[212:215], v[86:89]
	v_mfma_f32_16x16x32_bf16 v[76:79], v[170:173], v[212:215], v[76:79]
	v_mfma_f32_16x16x32_bf16 v[68:71], v[162:165], v[226:229], v[68:71]
	v_mfma_f32_16x16x32_bf16 v[64:67], v[170:173], v[226:229], v[64:67]
	s_setprio 0
.Lk0_half1:
	s_barrier
	s_add_i32 s85, s85, s39
	v_lshl_add_u64 v[182:183], s[6:7], 0, v[80:81]
	s_mov_b32 m0, s85
	ds_read_b128 v[174:177], v145 offset:16384
	ds_read_b128 v[178:181], v145 offset:17408
	ds_read_b128 v[200:203], v145 offset:18432
	ds_read_b128 v[204:207], v145 offset:19456
	ds_read_b128 v[208:211], v145 offset:20480
	ds_read_b128 v[212:215], v145 offset:21504
	ds_read_b128 v[222:225], v145 offset:22528
	ds_read_b128 v[226:229], v145 offset:23552
	global_load_lds_dwordx4 v[182:183], off
	s_add_i32 m0, s85, 0x2000
	s_add_u32 s86, s6, 0x40000
	v_lshl_add_u64 v[184:185], s[6:7], 0, v[130:131]
	s_addc_u32 s87, s7, 0
	s_add_i32 s85, s88, s39
	global_load_lds_dwordx4 v[184:185], off
	v_lshl_add_u64 v[188:189], s[86:87], 0, v[80:81]
	s_mov_b32 m0, s85
	v_lshl_add_u64 v[190:191], s[30:31], 0, v[132:133]
	global_load_lds_dwordx4 v[188:189], off
	v_lshl_add_u64 v[188:189], s[86:87], 0, v[130:131]
	s_add_i32 m0, s85, 0x2000
	s_nop 0
	global_load_lds_dwordx4 v[188:189], off
	v_lshl_add_u64 v[188:189], s[30:31], 0, v[134:135]
	s_mov_b32 m0, s60
	s_nop 0
	global_load_lds_dwordx4 v[188:189], off
	s_mov_b32 m0, s61
	s_nop 0
	global_load_lds_dwordx4 v[190:191], off
	s_waitcnt vmcnt(8)
	s_waitcnt lgkmcnt(0)
	s_barrier
	s_setprio 1
	s_waitcnt lgkmcnt(0)
	v_mfma_f32_16x16x32_bf16 v[60:63], v[140:143], v[174:177], v[60:63]
	v_mfma_f32_16x16x32_bf16 v[56:59], v[150:153], v[174:177], v[56:59]
	v_mfma_f32_16x16x32_bf16 v[48:51], v[140:143], v[200:203], v[48:51]
	v_mfma_f32_16x16x32_bf16 v[40:43], v[150:153], v[200:203], v[40:43]
	v_mfma_f32_16x16x32_bf16 v[32:35], v[140:143], v[208:211], v[32:35]
	v_mfma_f32_16x16x32_bf16 v[24:27], v[150:153], v[208:211], v[24:27]
	v_mfma_f32_16x16x32_bf16 v[16:19], v[140:143], v[222:225], v[16:19]
	v_mfma_f32_16x16x32_bf16 v[8:11], v[150:153], v[222:225], v[8:11]
	v_mfma_f32_16x16x32_bf16 v[60:63], v[146:149], v[178:181], v[60:63]
	v_mfma_f32_16x16x32_bf16 v[56:59], v[154:157], v[178:181], v[56:59]
	v_mfma_f32_16x16x32_bf16 v[48:51], v[146:149], v[204:207], v[48:51]
	v_mfma_f32_16x16x32_bf16 v[40:43], v[154:157], v[204:207], v[40:43]
	v_mfma_f32_16x16x32_bf16 v[32:35], v[146:149], v[212:215], v[32:35]
	v_mfma_f32_16x16x32_bf16 v[24:27], v[154:157], v[212:215], v[24:27]
	v_mfma_f32_16x16x32_bf16 v[16:19], v[146:149], v[226:229], v[16:19]
	v_mfma_f32_16x16x32_bf16 v[8:11], v[154:157], v[226:229], v[8:11]
	s_setprio 0
	s_cmp_eq_u32 s101, 1
	s_cbranch_scc1 .Lk0_half2
	s_setprio 1
	v_mfma_f32_16x16x32_bf16 v[52:55], v[158:161], v[174:177], v[52:55]
	v_mfma_f32_16x16x32_bf16 v[44:47], v[166:169], v[174:177], v[44:47]
	v_mfma_f32_16x16x32_bf16 v[36:39], v[158:161], v[200:203], v[36:39]
	v_mfma_f32_16x16x32_bf16 v[28:31], v[166:169], v[200:203], v[28:31]
	v_mfma_f32_16x16x32_bf16 v[20:23], v[158:161], v[208:211], v[20:23]
	v_mfma_f32_16x16x32_bf16 v[12:15], v[166:169], v[208:211], v[12:15]
	v_mfma_f32_16x16x32_bf16 v[4:7], v[158:161], v[222:225], v[4:7]
	v_mfma_f32_16x16x32_bf16 v[0:3], v[166:169], v[222:225], v[0:3]
	v_mfma_f32_16x16x32_bf16 v[52:55], v[162:165], v[178:181], v[52:55]
	v_mfma_f32_16x16x32_bf16 v[44:47], v[170:173], v[178:181], v[44:47]
	v_mfma_f32_16x16x32_bf16 v[36:39], v[162:165], v[204:207], v[36:39]
	v_mfma_f32_16x16x32_bf16 v[28:31], v[170:173], v[204:207], v[28:31]
	v_mfma_f32_16x16x32_bf16 v[20:23], v[162:165], v[212:215], v[20:23]
	v_mfma_f32_16x16x32_bf16 v[12:15], v[170:173], v[212:215], v[12:15]
	v_mfma_f32_16x16x32_bf16 v[4:7], v[162:165], v[226:229], v[4:7]
	v_mfma_f32_16x16x32_bf16 v[0:3], v[170:173], v[226:229], v[0:3]
	s_setprio 0
.Lk0_half2:
	s_barrier
	s_add_i32 s85, 0, 0x18000
	s_add_i32 s86, 0, 0x1c000
	v_add_u32_e32 v154, s85, v144
	v_add_u32_e32 v170, s86, v144
	ds_read_b128 v[140:143], v154
	ds_read_b128 v[146:149], v154 offset:1024
	ds_read_b128 v[150:153], v154 offset:2048
	ds_read_b128 v[154:157], v154 offset:3072
	ds_read_b128 v[158:161], v170
	ds_read_b128 v[162:165], v170 offset:1024
	ds_read_b128 v[166:169], v170 offset:2048
	ds_read_b128 v[170:173], v170 offset:3072
	s_add_u32 s30, s30, 0x40000
	s_addc_u32 s31, s31, 0
	s_mov_b32 m0, s62
	v_lshl_add_u64 v[192:193], s[30:31], 0, v[134:135]
	ds_read_b128 v[174:177], v145 offset:32768
	ds_read_b128 v[178:181], v145 offset:33792
	ds_read_b128 v[200:203], v145 offset:34816
	ds_read_b128 v[204:207], v145 offset:35840
	ds_read_b128 v[208:211], v145 offset:36864
	ds_read_b128 v[212:215], v145 offset:37888
	ds_read_b128 v[222:225], v145 offset:38912
	ds_read_b128 v[226:229], v145 offset:39936
	global_load_lds_dwordx4 v[192:193], off
	v_lshl_add_u64 v[192:193], s[30:31], 0, v[132:133]
	s_mov_b32 m0, s63
	s_nop 0
	global_load_lds_dwordx4 v[192:193], off
	s_waitcnt vmcnt(8)
	s_waitcnt lgkmcnt(0)
	s_barrier
	s_setprio 1
	s_waitcnt lgkmcnt(0)
	v_mfma_f32_16x16x32_bf16 v[126:129], v[140:143], v[174:177], v[126:129]
	v_mfma_f32_16x16x32_bf16 v[122:125], v[150:153], v[174:177], v[122:125]
	v_mfma_f32_16x16x32_bf16 v[114:117], v[140:143], v[200:203], v[114:117]
	v_mfma_f32_16x16x32_bf16 v[106:109], v[150:153], v[200:203], v[106:109]
	v_mfma_f32_16x16x32_bf16 v[98:101], v[140:143], v[208:211], v[98:101]
	v_mfma_f32_16x16x32_bf16 v[90:93], v[150:153], v[208:211], v[90:93]
	v_mfma_f32_16x16x32_bf16 v[82:85], v[140:143], v[222:225], v[82:85]
	v_mfma_f32_16x16x32_bf16 v[72:75], v[150:153], v[222:225], v[72:75]
	v_mfma_f32_16x16x32_bf16 v[126:129], v[146:149], v[178:181], v[126:129]
	v_mfma_f32_16x16x32_bf16 v[122:125], v[154:157], v[178:181], v[122:125]
	v_mfma_f32_16x16x32_bf16 v[114:117], v[146:149], v[204:207], v[114:117]
	v_mfma_f32_16x16x32_bf16 v[106:109], v[154:157], v[204:207], v[106:109]
	v_mfma_f32_16x16x32_bf16 v[98:101], v[146:149], v[212:215], v[98:101]
	v_mfma_f32_16x16x32_bf16 v[90:93], v[154:157], v[212:215], v[90:93]
	v_mfma_f32_16x16x32_bf16 v[82:85], v[146:149], v[226:229], v[82:85]
	v_mfma_f32_16x16x32_bf16 v[72:75], v[154:157], v[226:229], v[72:75]
	s_setprio 0
	s_cmp_eq_u32 s101, 1
	s_cbranch_scc1 .Lk0_half3
	s_setprio 1
	v_mfma_f32_16x16x32_bf16 v[118:121], v[158:161], v[174:177], v[118:121]
	v_mfma_f32_16x16x32_bf16 v[110:113], v[166:169], v[174:177], v[110:113]
	v_mfma_f32_16x16x32_bf16 v[102:105], v[158:161], v[200:203], v[102:105]
	v_mfma_f32_16x16x32_bf16 v[94:97], v[166:169], v[200:203], v[94:97]
	v_mfma_f32_16x16x32_bf16 v[86:89], v[158:161], v[208:211], v[86:89]
	v_mfma_f32_16x16x32_bf16 v[76:79], v[166:169], v[208:211], v[76:79]
	v_mfma_f32_16x16x32_bf16 v[68:71], v[158:161], v[222:225], v[68:71]
	v_mfma_f32_16x16x32_bf16 v[64:67], v[166:169], v[222:225], v[64:67]
	v_mfma_f32_16x16x32_bf16 v[118:121], v[162:165], v[178:181], v[118:121]
	v_mfma_f32_16x16x32_bf16 v[110:113], v[170:173], v[178:181], v[110:113]
	v_mfma_f32_16x16x32_bf16 v[102:105], v[162:165], v[204:207], v[102:105]
	v_mfma_f32_16x16x32_bf16 v[94:97], v[170:173], v[204:207], v[94:97]
	v_mfma_f32_16x16x32_bf16 v[86:89], v[162:165], v[212:215], v[86:89]
	v_mfma_f32_16x16x32_bf16 v[76:79], v[170:173], v[212:215], v[76:79]
	v_mfma_f32_16x16x32_bf16 v[68:71], v[162:165], v[226:229], v[68:71]
	v_mfma_f32_16x16x32_bf16 v[64:67], v[170:173], v[226:229], v[64:67]
	s_setprio 0
.Lk0_half3:
	s_barrier
	s_add_i32 s30, s85, s39
	v_lshl_add_u64 v[182:183], v[182:183], 0, s[12:13]
	s_mov_b32 m0, s30
	ds_read_b128 v[174:177], v145 offset:49152
	ds_read_b128 v[178:181], v145 offset:50176
	ds_read_b128 v[200:203], v145 offset:51200
	ds_read_b128 v[204:207], v145 offset:52224
	ds_read_b128 v[208:211], v145 offset:53248
	ds_read_b128 v[212:215], v145 offset:54272
	ds_read_b128 v[222:225], v145 offset:55296
	ds_read_b128 v[226:229], v145 offset:56320
	global_load_lds_dwordx4 v[182:183], off
	s_add_i32 m0, s30, 0x2000
	s_add_u32 s6, s6, 0x40080
	v_lshl_add_u64 v[182:183], v[184:185], 0, s[12:13]
	s_addc_u32 s7, s7, 0
	s_add_i32 s30, s86, s39
	global_load_lds_dwordx4 v[182:183], off
	v_lshl_add_u64 v[182:183], s[6:7], 0, v[80:81]
	s_mov_b32 m0, s30
	s_nop 0
	global_load_lds_dwordx4 v[182:183], off
	v_lshl_add_u64 v[182:183], s[6:7], 0, v[130:131]
	s_add_i32 m0, s30, 0x2000
	s_nop 0
	global_load_lds_dwordx4 v[182:183], off
	v_lshl_add_u64 v[182:183], v[188:189], 0, s[12:13]
	s_mov_b32 m0, s66
	s_nop 0
	global_load_lds_dwordx4 v[182:183], off
	v_lshl_add_u64 v[182:183], v[190:191], 0, s[12:13]
	s_mov_b32 m0, s67
	s_nop 0
	global_load_lds_dwordx4 v[182:183], off
	s_waitcnt vmcnt(8)
	s_waitcnt lgkmcnt(0)
	s_barrier
	s_setprio 1
	s_waitcnt lgkmcnt(0)
	v_mfma_f32_16x16x32_bf16 v[60:63], v[140:143], v[174:177], v[60:63]
	v_mfma_f32_16x16x32_bf16 v[56:59], v[150:153], v[174:177], v[56:59]
	v_mfma_f32_16x16x32_bf16 v[48:51], v[140:143], v[200:203], v[48:51]
	v_mfma_f32_16x16x32_bf16 v[40:43], v[150:153], v[200:203], v[40:43]
	v_mfma_f32_16x16x32_bf16 v[32:35], v[140:143], v[208:211], v[32:35]
	v_mfma_f32_16x16x32_bf16 v[24:27], v[150:153], v[208:211], v[24:27]
	v_mfma_f32_16x16x32_bf16 v[16:19], v[140:143], v[222:225], v[16:19]
	v_mfma_f32_16x16x32_bf16 v[8:11], v[150:153], v[222:225], v[8:11]
	v_mfma_f32_16x16x32_bf16 v[60:63], v[146:149], v[178:181], v[60:63]
	v_mfma_f32_16x16x32_bf16 v[56:59], v[154:157], v[178:181], v[56:59]
	v_mfma_f32_16x16x32_bf16 v[48:51], v[146:149], v[204:207], v[48:51]
	v_mfma_f32_16x16x32_bf16 v[40:43], v[154:157], v[204:207], v[40:43]
	v_mfma_f32_16x16x32_bf16 v[32:35], v[146:149], v[212:215], v[32:35]
	v_mfma_f32_16x16x32_bf16 v[24:27], v[154:157], v[212:215], v[24:27]
	v_mfma_f32_16x16x32_bf16 v[16:19], v[146:149], v[226:229], v[16:19]
	v_mfma_f32_16x16x32_bf16 v[8:11], v[154:157], v[226:229], v[8:11]
	s_setprio 0
	s_cmp_eq_u32 s101, 1
	s_cbranch_scc1 .Lk0_half4
	s_setprio 1
	v_mfma_f32_16x16x32_bf16 v[52:55], v[158:161], v[174:177], v[52:55]
	v_mfma_f32_16x16x32_bf16 v[44:47], v[166:169], v[174:177], v[44:47]
	v_mfma_f32_16x16x32_bf16 v[36:39], v[158:161], v[200:203], v[36:39]
	v_mfma_f32_16x16x32_bf16 v[28:31], v[166:169], v[200:203], v[28:31]
	v_mfma_f32_16x16x32_bf16 v[20:23], v[158:161], v[208:211], v[20:23]
	v_mfma_f32_16x16x32_bf16 v[12:15], v[166:169], v[208:211], v[12:15]
	v_mfma_f32_16x16x32_bf16 v[4:7], v[158:161], v[222:225], v[4:7]
	v_mfma_f32_16x16x32_bf16 v[0:3], v[166:169], v[222:225], v[0:3]
	v_mfma_f32_16x16x32_bf16 v[52:55], v[162:165], v[178:181], v[52:55]
	v_mfma_f32_16x16x32_bf16 v[44:47], v[170:173], v[178:181], v[44:47]
	v_mfma_f32_16x16x32_bf16 v[36:39], v[162:165], v[204:207], v[36:39]
	v_mfma_f32_16x16x32_bf16 v[28:31], v[170:173], v[204:207], v[28:31]
	v_mfma_f32_16x16x32_bf16 v[20:23], v[162:165], v[212:215], v[20:23]
	v_mfma_f32_16x16x32_bf16 v[12:15], v[170:173], v[212:215], v[12:15]
	v_mfma_f32_16x16x32_bf16 v[4:7], v[162:165], v[226:229], v[4:7]
	v_mfma_f32_16x16x32_bf16 v[0:3], v[170:173], v[226:229], v[0:3]
	s_setprio 0
.Lk0_half4:
	s_barrier
	s_add_i32 s84, s84, 2
	s_add_u32 s82, s82, 0x100
	s_addc_u32 s83, s83, 0
	s_add_u32 s0, s0, 0x100
	s_addc_u32 s1, s1, 0
	s_cmp_gt_u32 s84, 13
	s_cbranch_scc0 .LBB0_477
	s_and_b64 vcc, exec, s[10:11]
	s_cbranch_vccz .LBB0_480
	s_barrier
.LBB0_480:
	v_mbcnt_lo_u32_b32 v141, -1, 0
	v_mbcnt_hi_u32_b32 v141, -1, v141
	s_lshl_b32 s0, s78, 8
	s_cmp_lg_u32 s101, 1
	s_cbranch_scc1 .Lk0_e1
	s_bfe_u32 s1, s33, 0x10003
	s_lshl_b32 s1, s1, 7
	s_add_i32 s0, s0, s1
.Lk0_e1:
	v_ashrrev_i32_e32 v140, 1, v141
	v_and_or_b32 v141, v141, 15, s64
	v_and_b32_e32 v140, -8, v140
	s_or_b32 s0, s0, s65
	v_lshl_add_u32 v146, s77, 8, v141
	v_mov_b64_e32 v[142:143], s[8:9]
	v_add_u32_e32 v140, s0, v140
	v_mad_i64_i32 v[142:143], s[0:1], v146, s24, v[142:143]
	v_ashrrev_i32_e32 v141, 31, v140
	s_movk_i32 s0, 0x7c0
	v_lshl_add_u64 v[142:143], v[140:141], 1, v[142:143]
	v_cmp_gt_i32_e32 vcc, s0, v140
	s_and_saveexec_b64 s[0:1], vcc
	s_cbranch_execz .LBB0_482
	v_cvt_pk_bf16_f32 v126, v126, v127
	v_cvt_pk_bf16_f32 v127, v128, v129
	v_cvt_pk_bf16_f32 v128, v122, v123
	v_cvt_pk_bf16_f32 v129, v124, v125
	flat_store_dwordx4 v[142:143], v[126:129]
.LBB0_482:
	s_or_b64 exec, exec, s[0:1]
	s_movk_i32 s0, 0x740
	s_cmp_lg_u32 s101, 1
	s_cselect_b32 s0, s0, 0
	v_cmp_gt_i32_e64 s[0:1], s0, v140
	s_and_saveexec_b64 s[6:7], s[0:1]
	s_cbranch_execz .LBB0_484
	v_cvt_pk_bf16_f32 v118, v118, v119
	v_cvt_pk_bf16_f32 v119, v120, v121
	v_cvt_pk_bf16_f32 v120, v110, v111
	v_cvt_pk_bf16_f32 v121, v112, v113
	flat_store_dwordx4 v[142:143], v[118:121] offset:256

	.amdhsa_kernel _Z14fwd_megakernel4Args
		.amdhsa_group_segment_fixed_size 0
		.amdhsa_private_segment_fixed_size 0
		.amdhsa_kernarg_size 472
		.amdhsa_user_sgpr_count 2
		.amdhsa_user_sgpr_dispatch_ptr 0
		.amdhsa_user_sgpr_queue_ptr 0
		.amdhsa_user_sgpr_kernarg_segment_ptr 1
		.amdhsa_user_sgpr_dispatch_id 0
		.amdhsa_user_sgpr_kernarg_preload_length 0
		.amdhsa_user_sgpr_kernarg_preload_offset 0
		.amdhsa_user_sgpr_private_segment_size 0
		.amdhsa_uses_dynamic_stack 0
		.amdhsa_enable_private_segment 0
		.amdhsa_system_sgpr_workgroup_id_x 1
		.amdhsa_system_sgpr_workgroup_id_y 0
		.amdhsa_system_sgpr_workgroup_id_z 0
		.amdhsa_system_sgpr_workgroup_info 0
		.amdhsa_system_vgpr_workitem_id 2
		.amdhsa_next_free_vgpr 256
		.amdhsa_next_free_sgpr 102
		.amdhsa_accum_offset 256
		.amdhsa_reserve_vcc 1
		.amdhsa_float_round_mode_32 0
		.amdhsa_float_round_mode_16_64 0
		.amdhsa_float_denorm_mode_32 3
		.amdhsa_float_denorm_mode_16_64 3
		.amdhsa_dx10_clamp 1
		.amdhsa_ieee_mode 1
		.amdhsa_fp16_overflow 0
		.amdhsa_tg_split 0
		.amdhsa_exception_fp_ieee_invalid_op 0
		.amdhsa_exception_fp_denorm_src 0
		.amdhsa_exception_fp_ieee_div_zero 0
		.amdhsa_exception_fp_ieee_overflow 0
		.amdhsa_exception_fp_ieee_underflow 0
		.amdhsa_exception_fp_ieee_inexact 0
		.amdhsa_exception_int_div_zero 0
	.end_amdhsa_kernel

amdhsa.kernels:
  - .agpr_count:     0
    .args:
      - .offset:         0
        .size:           216
        .value_kind:     by_value
      - .offset:         216
        .size:           4
        .value_kind:     hidden_block_count_x
      - .offset:         220
        .size:           4
        .value_kind:     hidden_block_count_y
      - .offset:         224
        .size:           4
        .value_kind:     hidden_block_count_z
      - .offset:         228
        .size:           2
        .value_kind:     hidden_group_size_x
      - .offset:         230
        .size:           2
        .value_kind:     hidden_group_size_y
      - .offset:         232
        .size:           2
        .value_kind:     hidden_group_size_z
      - .offset:         234
        .size:           2
        .value_kind:     hidden_remainder_x
      - .offset:         236
        .size:           2
        .value_kind:     hidden_remainder_y
      - .offset:         238
        .size:           2
        .value_kind:     hidden_remainder_z
      - .offset:         256
        .size:           8
        .value_kind:     hidden_global_offset_x
      - .offset:         264
        .size:           8
        .value_kind:     hidden_global_offset_y
      - .offset:         272
        .size:           8
        .value_kind:     hidden_global_offset_z
      - .offset:         280
        .size:           2
        .value_kind:     hidden_grid_dims
      - .offset:         304
        .size:           8
        .value_kind:     hidden_multigrid_sync_arg
      - .offset:         336
        .size:           4
        .value_kind:     hidden_dynamic_lds_size
    .group_segment_fixed_size: 0
    .kernarg_segment_align: 8
    .kernarg_segment_size: 472
    .language:       OpenCL C
    .language_version:
      - 2
      - 0
    .max_flat_workgroup_size: 512
    .name:           _Z14fwd_megakernel4Args
    .private_segment_fixed_size: 0
    .sgpr_count:     108
    .sgpr_spill_count: 323
    .symbol:         _Z14fwd_megakernel4Args.kd
    .uniform_work_group_size: 1
    .uses_dynamic_stack: false
    .vgpr_count:     256
    .vgpr_spill_count: 0
    .wavefront_size: 64
